# phase 11: half of each XCD's workgroups start ~16 us later so main loops and memory-bound read-modify-write epilogues of the two halves interleave
# baseline (speedup 1.0000x reference)
.LBB0_378:
	s_and_b64 vcc, exec, s[6:7]
	s_cbranch_vccz .LBB0_488
	s_cmp_lg_u32 s57, 5
	s_cselect_b64 s[2:3], -1, 0
	s_cmp_eq_u32 s57, 5
	s_cselect_b32 s36, 2, 4
	s_mov_b32 s4, 0
	s_cbranch_scc1 .Lstag_done
	v_readlane_b32 s98, v249, 25
	s_nop 1
	s_bitcmp1_b32 s98, 6
	s_cbranch_scc0 .Lstag_done
	s_sleep 127
	s_sleep 127
	s_sleep 127
	s_sleep 127
.Lstag_done:
	s_branch .LBB0_382
.LBB0_380:
	s_waitcnt vmcnt(0)
	v_readlane_b32 s28, v254, 27
	s_mov_b64 s[40:41], s[72:73]
	v_readlane_b32 s29, v254, 28
	s_movk_i32 s26, 0x110
	s_mov_b32 s19, 0x400000
	s_mov_b64 s[42:43], s[74:75]
	s_barrier
